# grid barrier v2: last arriver of each of 8 groups bumps the polled group-complete word directly (one fewer atomic round trip)
# speedup vs baseline: 1.0251x; 1.0050x over previous
_Z14fwd_megakernel6Params:
	s_load_dwordx4 s[68:71], s[0:1], 0x80
	s_load_dwordx16 s[36:51], s[0:1], 0x0
	s_load_dwordx2 s[34:35], s[0:1], 0x90
	s_load_dwordx16 s[16:31], s[0:1], 0x40
	s_mov_b32 s12, s2
	s_waitcnt lgkmcnt(0)
	s_add_u32 s14, s70, 0x1f7a0000
	v_and_b32_e32 v1, 0x3ff, v0
	s_addc_u32 s15, s71, 0
	v_writelane_b32 v244, s16, 0
	s_sub_i32 s2, s35, s34
	s_cmp_lt_i32 s2, 2
	v_writelane_b32 v244, s17, 1
	v_writelane_b32 v244, s18, 2
	v_writelane_b32 v244, s19, 3
	v_writelane_b32 v244, s20, 4
	v_writelane_b32 v244, s21, 5
	v_writelane_b32 v244, s22, 6
	v_writelane_b32 v244, s23, 7
	v_writelane_b32 v244, s24, 8
	v_writelane_b32 v244, s25, 9
	v_writelane_b32 v244, s26, 10
	v_writelane_b32 v244, s27, 11
	v_writelane_b32 v244, s28, 12
	v_writelane_b32 v244, s29, 13
	v_writelane_b32 v244, s30, 14
	v_readfirstlane_b32 s10, v1
	v_writelane_b32 v244, s31, 15
	s_cbranch_scc1 .LBB0_14
	v_or_b32_e32 v2, s12, v1
	v_cmp_eq_u32_e32 vcc, 0, v2
	s_and_saveexec_b64 s[2:3], vcc
	s_cbranch_execz .LBB0_3
	v_mov_b32_e32 v2, 0
	global_store_dword v2, v2, s[14:15] sc1
	global_store_dword v2, v2, s[68:69] sc1
	global_store_dword v2, v2, s[68:69] offset:256 sc1
	global_store_dword v2, v2, s[68:69] offset:512 sc1
	global_store_dword v2, v2, s[68:69] offset:768 sc1
	global_store_dword v2, v2, s[68:69] offset:1024 sc1
	global_store_dword v2, v2, s[68:69] offset:1280 sc1
	global_store_dword v2, v2, s[68:69] offset:1536 sc1
	global_store_dword v2, v2, s[68:69] offset:1792 sc1
.LBB0_3:
	s_or_b64 exec, exec, s[2:3]
	v_lshrrev_b32_e32 v2, 20, v0
	v_lshrrev_b32_e32 v0, 10, v0
	v_or_b32_e32 v0, v0, v2
	s_movk_i32 s2, 0x3ff
	v_and_or_b32 v0, v0, s2, v1
	v_cmp_eq_u32_e32 vcc, 0, v0
	s_barrier
	s_and_saveexec_b64 s[2:3], vcc
	s_cbranch_execz .LBB0_13
	buffer_wbl2 sc1
	s_waitcnt vmcnt(0)
	s_load_dwordx2 s[4:5], s[0:1], 0xf0
	v_mov_b32_e32 v2, 0
	s_mov_b64 s[6:7], exec
	v_mbcnt_lo_u32_b32 v1, s6, 0
	v_mbcnt_hi_u32_b32 v1, s7, v1
	s_waitcnt lgkmcnt(0)
	global_load_dword v0, v2, s[4:5] offset:40
	v_cmp_eq_u32_e32 vcc, 0, v1
	s_and_saveexec_b64 s[8:9], vcc
	s_cbranch_execz .LBB0_6
	s_bcnt1_i32_b64 s6, s[6:7]
	v_mov_b32_e32 v3, s6
	global_atomic_add v3, v2, v3, s[4:5] offset:32 sc0

.LBB0_62:
	s_or_b64 exec, exec, s[2:3]
	s_cmp_lt_i32 s35, 2
	s_cbranch_scc1 .LBB0_71
	s_waitcnt vmcnt(1)
	v_mbcnt_lo_u32_b32 v0, -1, 0
	v_mbcnt_hi_u32_b32 v0, -1, v0
	s_waitcnt vmcnt(0) lgkmcnt(0)
	s_waitcnt lgkmcnt(0)
	v_add_u32_e32 v0, s84, v0
	v_cmp_gt_u32_e32 vcc, 64, v0
	s_barrier
	s_and_saveexec_b64 s[0:1], vcc
	s_cbranch_execz .LBB0_70
	buffer_wbl2 sc1
	s_waitcnt vmcnt(0)
	s_waitcnt vmcnt(0)
	v_cmp_eq_u32_e32 vcc, 0, v0
	s_and_saveexec_b64 s[2:3], vcc
	s_cbranch_execz .LBB0_69
	s_sub_i32 s4, 1, s34
	s_and_b32 s5, s12, 7
	s_sub_i32 s6, s13, s5
	s_add_i32 s6, s6, 7
	s_lshr_b32 s6, s6, 3
	s_mul_i32 s6, s6, s4
	s_lshl_b32 s5, s5, 8
	v_mov_b32_e32 v0, s5
	v_mov_b32_e32 v1, 1
	global_atomic_add v1, v0, v1, s[68:69] sc0
	s_min_u32 s7, s13, 8
	s_mul_i32 s4, s7, s4
	v_mov_b32_e32 v0, 0
	s_waitcnt vmcnt(0)
	v_add_u32_e32 v1, 1, v1
	v_cmp_eq_u32_e32 vcc, s6, v1
	s_cbranch_vccz .Lgb_spin_s0
	v_mov_b32_e32 v1, 1
	global_atomic_add v0, v1, s[14:15]

.LBB0_151:
	s_cmp_lt_i32 s35, 3
	s_cbranch_scc1 .LBB0_160
	v_mbcnt_lo_u32_b32 v0, -1, 0
	v_mbcnt_hi_u32_b32 v0, -1, v0
	s_waitcnt vmcnt(0) lgkmcnt(0)
	s_waitcnt vmcnt(0) lgkmcnt(0)
	v_add_u32_e32 v0, s84, v0
	v_cmp_gt_u32_e32 vcc, 64, v0
	s_barrier
	s_and_saveexec_b64 s[0:1], vcc
	s_cbranch_execz .LBB0_159
	buffer_wbl2 sc1
	s_waitcnt vmcnt(0)
	v_cmp_eq_u32_e32 vcc, 0, v0
	s_and_saveexec_b64 s[2:3], vcc
	s_cbranch_execz .LBB0_158
	s_sub_i32 s4, 2, s34
	s_and_b32 s5, s12, 7
	s_sub_i32 s6, s13, s5
	s_add_i32 s6, s6, 7
	s_lshr_b32 s6, s6, 3
	s_mul_i32 s6, s6, s4
	s_lshl_b32 s5, s5, 8
	v_mov_b32_e32 v0, s5
	v_mov_b32_e32 v1, 1
	global_atomic_add v1, v0, v1, s[68:69] sc0
	s_min_u32 s7, s13, 8
	s_mul_i32 s4, s7, s4
	v_mov_b32_e32 v0, 0
	s_waitcnt vmcnt(0)
	v_add_u32_e32 v1, 1, v1
	v_cmp_eq_u32_e32 vcc, s6, v1
	s_cbranch_vccz .Lgb_spin_s1
	v_mov_b32_e32 v1, 1
	global_atomic_add v0, v1, s[14:15]

.LBB0_211:
	s_cmp_eq_u32 s100, 1
	s_cbranch_scc1 .Ldil_ret12
	s_cmp_lt_i32 s35, 4
	s_cbranch_scc1 .LBB0_220
	v_mbcnt_lo_u32_b32 v0, -1, 0
	v_mbcnt_hi_u32_b32 v0, -1, v0
	s_waitcnt vmcnt(0) lgkmcnt(0)
	s_waitcnt lgkmcnt(0)
	v_add_u32_e32 v0, s84, v0
	v_cmp_gt_u32_e32 vcc, 64, v0
	s_barrier
	s_and_saveexec_b64 s[0:1], vcc
	s_cbranch_execz .LBB0_219
	buffer_wbl2 sc1
	s_waitcnt vmcnt(0)
	s_waitcnt vmcnt(0)
	v_cmp_eq_u32_e32 vcc, 0, v0
	s_and_saveexec_b64 s[2:3], vcc
	s_cbranch_execz .LBB0_218
	s_sub_i32 s4, 3, s34
	s_and_b32 s5, s12, 7
	s_sub_i32 s6, s13, s5
	s_add_i32 s6, s6, 7
	s_lshr_b32 s6, s6, 3
	s_mul_i32 s6, s6, s4
	s_lshl_b32 s5, s5, 8
	v_mov_b32_e32 v0, s5
	v_mov_b32_e32 v1, 1
	global_atomic_add v1, v0, v1, s[68:69] sc0
	s_min_u32 s7, s13, 8
	s_mul_i32 s4, s7, s4
	v_mov_b32_e32 v0, 0
	s_waitcnt vmcnt(0)
	v_add_u32_e32 v1, 1, v1
	v_cmp_eq_u32_e32 vcc, s6, v1
	s_cbranch_vccz .Lgb_spin_s2
	v_mov_b32_e32 v1, 1
	global_atomic_add v0, v1, s[14:15]

.LBB0_245:
	s_cmp_lt_i32 s35, 5
	s_cbranch_scc1 .LBB0_254
	v_mbcnt_lo_u32_b32 v0, -1, 0
	v_mbcnt_hi_u32_b32 v0, -1, v0
	s_waitcnt vmcnt(0) lgkmcnt(0)
	s_waitcnt vmcnt(0) lgkmcnt(0)
	v_add_u32_e32 v0, s84, v0
	v_cmp_gt_u32_e32 vcc, 64, v0
	s_barrier
	s_and_saveexec_b64 s[0:1], vcc
	s_cbranch_execz .LBB0_253
	buffer_wbl2 sc1
	s_waitcnt vmcnt(0)
	v_cmp_eq_u32_e32 vcc, 0, v0
	s_and_saveexec_b64 s[2:3], vcc
	s_cbranch_execz .LBB0_252
	s_sub_i32 s4, 4, s34
	s_and_b32 s5, s12, 7
	s_sub_i32 s6, s13, s5
	s_add_i32 s6, s6, 7
	s_lshr_b32 s6, s6, 3
	s_mul_i32 s6, s6, s4
	s_lshl_b32 s5, s5, 8
	v_mov_b32_e32 v0, s5
	v_mov_b32_e32 v1, 1
	global_atomic_add v1, v0, v1, s[68:69] sc0
	s_min_u32 s7, s13, 8
	s_mul_i32 s4, s7, s4
	v_mov_b32_e32 v0, 0
	s_waitcnt vmcnt(0)
	v_add_u32_e32 v1, 1, v1
	v_cmp_eq_u32_e32 vcc, s6, v1
	s_cbranch_vccz .Lgb_spin_s3
	v_mov_b32_e32 v1, 1
	global_atomic_add v0, v1, s[14:15]

.LBB0_289:
	s_cmp_eq_u32 s99, 1
	s_cbranch_scc1 .Lmla_ret14
	s_cmp_lt_i32 s35, 6
	s_cbranch_scc1 .LBB0_298
	v_mbcnt_lo_u32_b32 v0, -1, 0
	v_mbcnt_hi_u32_b32 v0, -1, v0
	s_waitcnt vmcnt(0) lgkmcnt(0)
	s_waitcnt lgkmcnt(0)
	v_add_u32_e32 v0, s84, v0
	v_cmp_gt_u32_e32 vcc, 64, v0
	s_barrier
	s_and_saveexec_b64 s[0:1], vcc
	s_cbranch_execz .LBB0_297
	buffer_wbl2 sc1
	s_waitcnt vmcnt(0)
	s_waitcnt vmcnt(0)
	v_cmp_eq_u32_e32 vcc, 0, v0
	s_and_saveexec_b64 s[2:3], vcc
	s_cbranch_execz .LBB0_296
	s_sub_i32 s4, 5, s34
	s_and_b32 s5, s12, 7
	s_sub_i32 s6, s13, s5
	s_add_i32 s6, s6, 7
	s_lshr_b32 s6, s6, 3
	s_mul_i32 s6, s6, s4
	s_lshl_b32 s5, s5, 8
	v_mov_b32_e32 v0, s5
	v_mov_b32_e32 v1, 1
	global_atomic_add v1, v0, v1, s[68:69] sc0
	s_min_u32 s7, s13, 8
	s_mul_i32 s4, s7, s4
	v_mov_b32_e32 v0, 0
	s_waitcnt vmcnt(0)
	v_add_u32_e32 v1, 1, v1
	v_cmp_eq_u32_e32 vcc, s6, v1
	s_cbranch_vccz .Lgb_spin_s4
	v_mov_b32_e32 v1, 1
	global_atomic_add v0, v1, s[14:15]

.LBB0_302:
	s_or_b64 exec, exec, s[2:3]
	s_cmp_lt_u32 s35, 7
	s_cbranch_scc1 .LBB0_311
	v_mbcnt_lo_u32_b32 v0, -1, 0
	v_mbcnt_hi_u32_b32 v0, -1, v0
	s_waitcnt vmcnt(0) lgkmcnt(0)
	s_waitcnt lgkmcnt(0)
	v_add_u32_e32 v0, s84, v0
	v_cmp_gt_u32_e32 vcc, 64, v0
	s_barrier
	s_and_saveexec_b64 s[0:1], vcc
	s_cbranch_execz .LBB0_310
	buffer_wbl2 sc1
	s_waitcnt vmcnt(0)
	s_waitcnt vmcnt(0)
	v_cmp_eq_u32_e32 vcc, 0, v0
	s_and_saveexec_b64 s[2:3], vcc
	s_cbranch_execz .LBB0_309
	s_sub_i32 s4, 6, s34
	s_and_b32 s5, s12, 7
	s_sub_i32 s6, s13, s5
	s_add_i32 s6, s6, 7
	s_lshr_b32 s6, s6, 3
	s_mul_i32 s6, s6, s4
	s_lshl_b32 s5, s5, 8
	v_mov_b32_e32 v0, s5
	v_mov_b32_e32 v1, 1
	global_atomic_add v1, v0, v1, s[68:69] sc0
	s_min_u32 s7, s13, 8
	s_mul_i32 s4, s7, s4
	v_mov_b32_e32 v0, 0
	s_waitcnt vmcnt(0)
	v_add_u32_e32 v1, 1, v1
	v_cmp_eq_u32_e32 vcc, s6, v1
	s_cbranch_vccz .Lgb_spin_s5
	v_mov_b32_e32 v1, 1
	global_atomic_add v0, v1, s[14:15]

.LBB0_327:
	s_cmp_lt_i32 s35, 8
	s_cbranch_scc1 .LBB0_336
	v_mbcnt_lo_u32_b32 v0, -1, 0
	v_mbcnt_hi_u32_b32 v0, -1, v0
	s_waitcnt vmcnt(0) lgkmcnt(0)
	s_waitcnt vmcnt(0) lgkmcnt(0)
	v_add_u32_e32 v0, s84, v0
	v_cmp_gt_u32_e32 vcc, 64, v0
	s_barrier
	s_and_saveexec_b64 s[0:1], vcc
	s_cbranch_execz .LBB0_335
	buffer_wbl2 sc1
	s_waitcnt vmcnt(0)
	v_cmp_eq_u32_e32 vcc, 0, v0
	s_and_saveexec_b64 s[2:3], vcc
	s_cbranch_execz .LBB0_334
	s_sub_i32 s4, 7, s34
	s_and_b32 s5, s12, 7
	s_sub_i32 s6, s13, s5
	s_add_i32 s6, s6, 7
	s_lshr_b32 s6, s6, 3
	s_mul_i32 s6, s6, s4
	s_lshl_b32 s5, s5, 8
	v_mov_b32_e32 v0, s5
	v_mov_b32_e32 v1, 1
	global_atomic_add v1, v0, v1, s[68:69] sc0
	s_min_u32 s7, s13, 8
	s_mul_i32 s4, s7, s4
	v_mov_b32_e32 v0, 0
	s_waitcnt vmcnt(0)
	v_add_u32_e32 v1, 1, v1
	v_cmp_eq_u32_e32 vcc, s6, v1
	s_cbranch_vccz .Lgb_spin_s6
	v_mov_b32_e32 v1, 1
	global_atomic_add v0, v1, s[14:15]

.LBB0_348:
	s_or_b64 exec, exec, s[2:3]
	s_cmp_lt_i32 s35, 9
	s_cbranch_scc1 .LBB0_357
	v_mbcnt_lo_u32_b32 v0, -1, 0
	v_mbcnt_hi_u32_b32 v0, -1, v0
	s_waitcnt vmcnt(0) lgkmcnt(0)
	s_waitcnt lgkmcnt(0)
	v_add_u32_e32 v0, s84, v0
	v_cmp_gt_u32_e32 vcc, 64, v0
	s_barrier
	s_and_saveexec_b64 s[0:1], vcc
	s_cbranch_execz .LBB0_356
	buffer_wbl2 sc1
	s_waitcnt vmcnt(0)
	s_waitcnt vmcnt(0)
	v_cmp_eq_u32_e32 vcc, 0, v0
	s_and_saveexec_b64 s[2:3], vcc
	s_cbranch_execz .LBB0_355
	s_sub_i32 s4, 8, s34
	s_and_b32 s5, s12, 7
	s_sub_i32 s6, s13, s5
	s_add_i32 s6, s6, 7
	s_lshr_b32 s6, s6, 3
	s_mul_i32 s6, s6, s4
	s_lshl_b32 s5, s5, 8
	v_mov_b32_e32 v0, s5
	v_mov_b32_e32 v1, 1
	global_atomic_add v1, v0, v1, s[68:69] sc0
	s_min_u32 s7, s13, 8
	s_mul_i32 s4, s7, s4
	v_mov_b32_e32 v0, 0
	s_waitcnt vmcnt(0)
	v_add_u32_e32 v1, 1, v1
	v_cmp_eq_u32_e32 vcc, s6, v1
	s_cbranch_vccz .Lgb_spin_s7
	v_mov_b32_e32 v1, 1
	global_atomic_add v0, v1, s[14:15]

.LBB0_373:
	s_cmp_lt_i32 s35, 10
	s_cbranch_scc1 .LBB0_382
	v_mbcnt_lo_u32_b32 v0, -1, 0
	v_mbcnt_hi_u32_b32 v0, -1, v0
	s_waitcnt vmcnt(0) lgkmcnt(0)
	s_waitcnt vmcnt(0) lgkmcnt(0)
	v_add_u32_e32 v0, s84, v0
	v_cmp_gt_u32_e32 vcc, 64, v0
	s_barrier
	s_and_saveexec_b64 s[0:1], vcc
	s_cbranch_execz .LBB0_381
	buffer_wbl2 sc1
	s_waitcnt vmcnt(0)
	v_cmp_eq_u32_e32 vcc, 0, v0
	s_and_saveexec_b64 s[2:3], vcc
	s_cbranch_execz .LBB0_380
	s_sub_i32 s4, 9, s34
	s_and_b32 s5, s12, 7
	s_sub_i32 s6, s13, s5
	s_add_i32 s6, s6, 7
	s_lshr_b32 s6, s6, 3
	s_mul_i32 s6, s6, s4
	s_lshl_b32 s5, s5, 8
	v_mov_b32_e32 v0, s5
	v_mov_b32_e32 v1, 1
	global_atomic_add v1, v0, v1, s[68:69] sc0
	s_min_u32 s7, s13, 8
	s_mul_i32 s4, s7, s4
	v_mov_b32_e32 v0, 0
	s_waitcnt vmcnt(0)
	v_add_u32_e32 v1, 1, v1
	v_cmp_eq_u32_e32 vcc, s6, v1
	s_cbranch_vccz .Lgb_spin_s8
	v_mov_b32_e32 v1, 1
	global_atomic_add v0, v1, s[14:15]

.LBB0_398:
	s_cmp_lt_i32 s35, 11
	s_cbranch_scc1 .LBB0_407
	v_mbcnt_lo_u32_b32 v0, -1, 0
	v_mbcnt_hi_u32_b32 v0, -1, v0
	s_waitcnt vmcnt(0) lgkmcnt(0)
	s_waitcnt vmcnt(0) lgkmcnt(0)
	v_add_u32_e32 v0, s84, v0
	v_cmp_gt_u32_e32 vcc, 64, v0
	s_barrier
	s_and_saveexec_b64 s[0:1], vcc
	s_cbranch_execz .LBB0_406
	buffer_wbl2 sc1
	s_waitcnt vmcnt(0)
	v_cmp_eq_u32_e32 vcc, 0, v0
	s_and_saveexec_b64 s[2:3], vcc
	s_cbranch_execz .LBB0_405
	s_sub_i32 s4, 10, s34
	s_and_b32 s5, s12, 7
	s_sub_i32 s6, s13, s5
	s_add_i32 s6, s6, 7
	s_lshr_b32 s6, s6, 3
	s_mul_i32 s6, s6, s4
	s_lshl_b32 s5, s5, 8
	v_mov_b32_e32 v0, s5
	v_mov_b32_e32 v1, 1
	global_atomic_add v1, v0, v1, s[68:69] sc0
	s_min_u32 s7, s13, 8
	s_mul_i32 s4, s7, s4
	v_mov_b32_e32 v0, 0
	s_waitcnt vmcnt(0)
	v_add_u32_e32 v1, 1, v1
	v_cmp_eq_u32_e32 vcc, s6, v1
	s_cbranch_vccz .Lgb_spin_s9
	v_mov_b32_e32 v1, 1
	global_atomic_add v0, v1, s[14:15]

.LBB0_442:
	s_or_b64 exec, exec, s[0:1]
	s_cmp_lt_i32 s35, 12
	s_cbranch_scc1 .LBB0_451
	v_mbcnt_lo_u32_b32 v0, -1, 0
	v_mbcnt_hi_u32_b32 v0, -1, v0
	s_waitcnt vmcnt(0) lgkmcnt(0)
	s_waitcnt lgkmcnt(0)
	v_add_u32_e32 v0, s84, v0
	v_cmp_gt_u32_e32 vcc, 64, v0
	s_barrier
	s_and_saveexec_b64 s[0:1], vcc
	s_cbranch_execz .LBB0_450
	buffer_wbl2 sc1
	s_waitcnt vmcnt(0)
	s_waitcnt vmcnt(0)
	v_cmp_eq_u32_e32 vcc, 0, v0
	s_and_saveexec_b64 s[2:3], vcc
	s_cbranch_execz .LBB0_449
	s_sub_i32 s4, 11, s34
	s_and_b32 s5, s12, 7
	s_sub_i32 s6, s13, s5
	s_add_i32 s6, s6, 7
	s_lshr_b32 s6, s6, 3
	s_mul_i32 s6, s6, s4
	s_lshl_b32 s5, s5, 8
	v_mov_b32_e32 v0, s5
	v_mov_b32_e32 v1, 1
	global_atomic_add v1, v0, v1, s[68:69] sc0
	s_min_u32 s7, s13, 8
	s_mul_i32 s4, s7, s4
	v_mov_b32_e32 v0, 0
	s_waitcnt vmcnt(0)
	v_add_u32_e32 v1, 1, v1
	v_cmp_eq_u32_e32 vcc, s6, v1
	s_cbranch_vccz .Lgb_spin_s10
	v_mov_b32_e32 v1, 1
	global_atomic_add v0, v1, s[14:15]

.LBB0_531:
	s_cmp_lt_i32 s35, 13
	s_cbranch_scc1 .LBB0_540
	v_mbcnt_lo_u32_b32 v0, -1, 0
	v_mbcnt_hi_u32_b32 v0, -1, v0
	s_waitcnt vmcnt(0) lgkmcnt(0)
	s_waitcnt vmcnt(0) lgkmcnt(0)
	v_add_u32_e32 v0, s84, v0
	v_cmp_gt_u32_e32 vcc, 64, v0
	s_barrier
	s_and_saveexec_b64 s[0:1], vcc
	s_cbranch_execz .LBB0_539
	buffer_wbl2 sc1
	s_waitcnt vmcnt(0)
	v_cmp_eq_u32_e32 vcc, 0, v0
	s_and_saveexec_b64 s[2:3], vcc
	s_cbranch_execz .LBB0_538
	s_sub_i32 s4, 12, s34
	s_and_b32 s5, s12, 7
	s_sub_i32 s6, s13, s5
	s_add_i32 s6, s6, 7
	s_lshr_b32 s6, s6, 3
	s_mul_i32 s6, s6, s4
	s_lshl_b32 s5, s5, 8
	v_mov_b32_e32 v0, s5
	v_mov_b32_e32 v1, 1
	global_atomic_add v1, v0, v1, s[68:69] sc0
	s_min_u32 s7, s13, 8
	s_mul_i32 s4, s7, s4
	v_mov_b32_e32 v0, 0
	s_waitcnt vmcnt(0)
	v_add_u32_e32 v1, 1, v1
	v_cmp_eq_u32_e32 vcc, s6, v1
	s_cbranch_vccz .Lgb_spin_s11
	v_mov_b32_e32 v1, 1
	global_atomic_add v0, v1, s[14:15]

.Ldil_ret12:
.LBB0_590:
	s_cmp_lt_i32 s35, 14
	s_cbranch_scc1 .LBB0_599
	v_mbcnt_lo_u32_b32 v0, -1, 0
	v_mbcnt_hi_u32_b32 v0, -1, v0
	s_waitcnt vmcnt(0) lgkmcnt(0)
	s_waitcnt lgkmcnt(0)
	v_add_u32_e32 v0, s84, v0
	v_cmp_gt_u32_e32 vcc, 64, v0
	s_barrier
	s_and_saveexec_b64 s[0:1], vcc
	s_cbranch_execz .LBB0_598
	buffer_wbl2 sc1
	s_waitcnt vmcnt(0)
	s_waitcnt vmcnt(0)
	v_cmp_eq_u32_e32 vcc, 0, v0
	s_and_saveexec_b64 s[2:3], vcc
	s_cbranch_execz .LBB0_597
	s_sub_i32 s4, 13, s34
	s_and_b32 s5, s12, 7
	s_sub_i32 s6, s13, s5
	s_add_i32 s6, s6, 7
	s_lshr_b32 s6, s6, 3
	s_mul_i32 s6, s6, s4
	s_lshl_b32 s5, s5, 8
	v_mov_b32_e32 v0, s5
	v_mov_b32_e32 v1, 1
	global_atomic_add v1, v0, v1, s[68:69] sc0
	s_min_u32 s7, s13, 8
	s_mul_i32 s4, s7, s4
	v_mov_b32_e32 v0, 0
	s_waitcnt vmcnt(0)
	v_add_u32_e32 v1, 1, v1
	v_cmp_eq_u32_e32 vcc, s6, v1
	s_cbranch_vccz .Lgb_spin_s12
	v_mov_b32_e32 v1, 1
	global_atomic_add v0, v1, s[14:15]

.LBB0_624:
	s_cmp_lt_i32 s35, 15
	s_cbranch_scc1 .LBB0_633
	v_mbcnt_lo_u32_b32 v0, -1, 0
	v_mbcnt_hi_u32_b32 v0, -1, v0
	s_waitcnt vmcnt(0) lgkmcnt(0)
	s_waitcnt vmcnt(0) lgkmcnt(0)
	v_add_u32_e32 v0, s84, v0
	v_cmp_gt_u32_e32 vcc, 64, v0
	s_barrier
	s_and_saveexec_b64 s[0:1], vcc
	s_cbranch_execz .LBB0_632
	buffer_wbl2 sc1
	s_waitcnt vmcnt(0)
	v_cmp_eq_u32_e32 vcc, 0, v0
	s_and_saveexec_b64 s[2:3], vcc
	s_cbranch_execz .LBB0_631
	s_sub_i32 s4, 14, s34
	s_and_b32 s5, s12, 7
	s_sub_i32 s6, s13, s5
	s_add_i32 s6, s6, 7
	s_lshr_b32 s6, s6, 3
	s_mul_i32 s6, s6, s4
	s_lshl_b32 s5, s5, 8
	v_mov_b32_e32 v0, s5
	v_mov_b32_e32 v1, 1
	global_atomic_add v1, v0, v1, s[68:69] sc0
	s_min_u32 s7, s13, 8
	s_mul_i32 s4, s7, s4
	v_mov_b32_e32 v0, 0
	s_waitcnt vmcnt(0)
	v_add_u32_e32 v1, 1, v1
	v_cmp_eq_u32_e32 vcc, s6, v1
	s_cbranch_vccz .Lgb_spin_s13
	v_mov_b32_e32 v1, 1
	global_atomic_add v0, v1, s[14:15]

.Lmla_ret14:
.LBB0_668:
	s_cmp_lt_i32 s35, 16
	s_cbranch_scc1 .LBB0_677
	v_mbcnt_lo_u32_b32 v0, -1, 0
	v_mbcnt_hi_u32_b32 v0, -1, v0
	s_waitcnt vmcnt(0) lgkmcnt(0)
	s_waitcnt lgkmcnt(0)
	v_add_u32_e32 v0, s84, v0
	v_cmp_gt_u32_e32 vcc, 64, v0
	s_barrier
	s_and_saveexec_b64 s[0:1], vcc
	s_cbranch_execz .LBB0_676
	buffer_wbl2 sc1
	s_waitcnt vmcnt(0)
	s_waitcnt vmcnt(0)
	v_cmp_eq_u32_e32 vcc, 0, v0
	s_and_saveexec_b64 s[2:3], vcc
	s_cbranch_execz .LBB0_675
	s_sub_i32 s4, 15, s34
	s_and_b32 s5, s12, 7
	s_sub_i32 s6, s13, s5
	s_add_i32 s6, s6, 7
	s_lshr_b32 s6, s6, 3
	s_mul_i32 s6, s6, s4
	s_lshl_b32 s5, s5, 8
	v_mov_b32_e32 v0, s5
	v_mov_b32_e32 v1, 1
	global_atomic_add v1, v0, v1, s[68:69] sc0
	s_min_u32 s7, s13, 8
	s_mul_i32 s4, s7, s4
	v_mov_b32_e32 v0, 0
	s_waitcnt vmcnt(0)
	v_add_u32_e32 v1, 1, v1
	v_cmp_eq_u32_e32 vcc, s6, v1
	s_cbranch_vccz .Lgb_spin_s14
	v_mov_b32_e32 v1, 1
	global_atomic_add v0, v1, s[14:15]

.LBB0_681:
	s_or_b64 exec, exec, s[2:3]
	s_cmp_lt_u32 s35, 17
	s_cbranch_scc1 .LBB0_690
	v_mbcnt_lo_u32_b32 v0, -1, 0
	v_mbcnt_hi_u32_b32 v0, -1, v0
	s_waitcnt vmcnt(0) lgkmcnt(0)
	s_waitcnt lgkmcnt(0)
	v_add_u32_e32 v0, s84, v0
	v_cmp_gt_u32_e32 vcc, 64, v0
	s_barrier
	s_and_saveexec_b64 s[0:1], vcc
	s_cbranch_execz .LBB0_689
	buffer_wbl2 sc1
	s_waitcnt vmcnt(0)
	s_waitcnt vmcnt(0)
	v_cmp_eq_u32_e32 vcc, 0, v0
	s_and_saveexec_b64 s[2:3], vcc
	s_cbranch_execz .LBB0_688
	s_sub_i32 s4, 16, s34
	s_and_b32 s5, s12, 7
	s_sub_i32 s6, s13, s5
	s_add_i32 s6, s6, 7
	s_lshr_b32 s6, s6, 3
	s_mul_i32 s6, s6, s4
	s_lshl_b32 s5, s5, 8
	v_mov_b32_e32 v0, s5
	v_mov_b32_e32 v1, 1
	global_atomic_add v1, v0, v1, s[68:69] sc0
	s_min_u32 s7, s13, 8
	s_mul_i32 s4, s7, s4
	v_mov_b32_e32 v0, 0
	s_waitcnt vmcnt(0)
	v_add_u32_e32 v1, 1, v1
	v_cmp_eq_u32_e32 vcc, s6, v1
	s_cbranch_vccz .Lgb_spin_s15
	v_mov_b32_e32 v1, 1
	global_atomic_add v0, v1, s[14:15]

.LBB0_706:
	s_cmp_lt_i32 s35, 18
	s_cbranch_scc1 .LBB0_715
	v_mbcnt_lo_u32_b32 v0, -1, 0
	v_mbcnt_hi_u32_b32 v0, -1, v0
	s_waitcnt vmcnt(0) lgkmcnt(0)
	s_waitcnt vmcnt(0) lgkmcnt(0)
	v_add_u32_e32 v0, s84, v0
	v_cmp_gt_u32_e32 vcc, 64, v0
	s_barrier
	s_and_saveexec_b64 s[0:1], vcc
	s_cbranch_execz .LBB0_714
	buffer_wbl2 sc1
	s_waitcnt vmcnt(0)
	v_cmp_eq_u32_e32 vcc, 0, v0
	s_and_saveexec_b64 s[2:3], vcc
	s_cbranch_execz .LBB0_713
	s_sub_i32 s4, 17, s34
	s_and_b32 s5, s12, 7
	s_sub_i32 s6, s13, s5
	s_add_i32 s6, s6, 7
	s_lshr_b32 s6, s6, 3
	s_mul_i32 s6, s6, s4
	s_lshl_b32 s5, s5, 8
	v_mov_b32_e32 v0, s5
	v_mov_b32_e32 v1, 1
	global_atomic_add v1, v0, v1, s[68:69] sc0
	s_min_u32 s7, s13, 8
	s_mul_i32 s4, s7, s4
	v_mov_b32_e32 v0, 0
	s_waitcnt vmcnt(0)
	v_add_u32_e32 v1, 1, v1
	v_cmp_eq_u32_e32 vcc, s6, v1
	s_cbranch_vccz .Lgb_spin_s16
	v_mov_b32_e32 v1, 1
	global_atomic_add v0, v1, s[14:15]

.LBB0_719:
	s_or_b64 exec, exec, s[0:1]
	s_cmp_lt_u32 s35, 19
	s_cbranch_scc1 .LBB0_728
	v_mbcnt_lo_u32_b32 v0, -1, 0
	v_mbcnt_hi_u32_b32 v0, -1, v0
	s_waitcnt vmcnt(0) lgkmcnt(0)
	s_nop 0
	v_add_u32_e32 v0, s84, v0
	v_cmp_gt_u32_e32 vcc, 64, v0
	s_barrier
	s_and_saveexec_b64 s[0:1], vcc
	s_cbranch_execz .LBB0_727
	buffer_wbl2 sc1
	s_waitcnt vmcnt(0)
	s_waitcnt vmcnt(0)
	v_cmp_eq_u32_e32 vcc, 0, v0
	s_and_saveexec_b64 s[2:3], vcc
	s_cbranch_execz .LBB0_726
	s_sub_i32 s4, 18, s34
	s_and_b32 s5, s12, 7
	s_sub_i32 s6, s13, s5
	s_add_i32 s6, s6, 7
	s_lshr_b32 s6, s6, 3
	s_mul_i32 s6, s6, s4
	s_lshl_b32 s5, s5, 8
	v_mov_b32_e32 v0, s5
	v_mov_b32_e32 v1, 1
	global_atomic_add v1, v0, v1, s[68:69] sc0
	s_min_u32 s7, s13, 8
	s_mul_i32 s4, s7, s4
	v_mov_b32_e32 v0, 0
	s_waitcnt vmcnt(0)
	v_add_u32_e32 v1, 1, v1
	v_cmp_eq_u32_e32 vcc, s6, v1
	s_cbranch_vccz .Lgb_spin_s17
	v_mov_b32_e32 v1, 1
	global_atomic_add v0, v1, s[14:15]

.LBB0_744:
	s_cmp_lt_i32 s35, 20
	s_cbranch_scc1 .LBB0_753
	v_mbcnt_lo_u32_b32 v0, -1, 0
	v_mbcnt_hi_u32_b32 v0, -1, v0
	s_waitcnt vmcnt(0) lgkmcnt(0)
	s_waitcnt vmcnt(0) lgkmcnt(0)
	v_add_u32_e32 v0, s84, v0
	v_cmp_gt_u32_e32 vcc, 64, v0
	s_barrier
	s_and_saveexec_b64 s[0:1], vcc
	s_cbranch_execz .LBB0_752
	buffer_wbl2 sc1
	s_waitcnt vmcnt(0)
	v_cmp_eq_u32_e32 vcc, 0, v0
	s_and_saveexec_b64 s[2:3], vcc
	s_cbranch_execz .LBB0_751
	s_sub_i32 s4, 19, s34
	s_and_b32 s5, s12, 7
	s_sub_i32 s6, s13, s5
	s_add_i32 s6, s6, 7
	s_lshr_b32 s6, s6, 3
	s_mul_i32 s6, s6, s4
	s_lshl_b32 s5, s5, 8
	v_mov_b32_e32 v0, s5
	v_mov_b32_e32 v1, 1
	global_atomic_add v1, v0, v1, s[68:69] sc0
	s_min_u32 s7, s13, 8
	s_mul_i32 s4, s7, s4
	v_mov_b32_e32 v0, 0
	s_waitcnt vmcnt(0)
	v_add_u32_e32 v1, 1, v1
	v_cmp_eq_u32_e32 vcc, s6, v1
	s_cbranch_vccz .Lgb_spin_s18
	v_mov_b32_e32 v1, 1
	global_atomic_add v0, v1, s[14:15]

.LBB0_769:
	s_cmp_lt_i32 s35, 21
	s_cbranch_scc1 .LBB0_778
	v_mbcnt_lo_u32_b32 v0, -1, 0
	v_mbcnt_hi_u32_b32 v0, -1, v0
	s_waitcnt vmcnt(0) lgkmcnt(0)
	s_waitcnt vmcnt(0) lgkmcnt(0)
	v_add_u32_e32 v0, s84, v0
	v_cmp_gt_u32_e32 vcc, 64, v0
	s_barrier
	s_and_saveexec_b64 s[0:1], vcc
	s_cbranch_execz .LBB0_777
	buffer_wbl2 sc1
	s_waitcnt vmcnt(0)
	v_cmp_eq_u32_e32 vcc, 0, v0
	s_and_saveexec_b64 s[2:3], vcc
	s_cbranch_execz .LBB0_776
	s_sub_i32 s4, 20, s34
	s_and_b32 s5, s12, 7
	s_sub_i32 s6, s13, s5
	s_add_i32 s6, s6, 7
	s_lshr_b32 s6, s6, 3
	s_mul_i32 s6, s6, s4
	s_lshl_b32 s5, s5, 8
	v_mov_b32_e32 v0, s5
	v_mov_b32_e32 v1, 1
	global_atomic_add v1, v0, v1, s[68:69] sc0
	s_min_u32 s7, s13, 8
	s_mul_i32 s4, s7, s4
	v_mov_b32_e32 v0, 0
	s_waitcnt vmcnt(0)
	v_add_u32_e32 v1, 1, v1
	v_cmp_eq_u32_e32 vcc, s6, v1
	s_cbranch_vccz .Lgb_spin_s19
	v_mov_b32_e32 v1, 1
	global_atomic_add v0, v1, s[14:15]

.LBB0_782:
	s_or_b64 exec, exec, s[0:1]
	s_cmp_lt_u32 s35, 22
	s_cbranch_scc1 .LBB0_791
	v_mbcnt_lo_u32_b32 v0, -1, 0
	v_mbcnt_hi_u32_b32 v0, -1, v0
	s_waitcnt vmcnt(0) lgkmcnt(0)
	s_waitcnt lgkmcnt(0)
	v_add_u32_e32 v0, s84, v0
	v_cmp_gt_u32_e32 vcc, 64, v0
	s_barrier
	s_and_saveexec_b64 s[0:1], vcc
	s_cbranch_execz .LBB0_790
	buffer_wbl2 sc1
	s_waitcnt vmcnt(0)
	s_waitcnt vmcnt(0)
	v_cmp_eq_u32_e32 vcc, 0, v0
	s_and_saveexec_b64 s[2:3], vcc
	s_cbranch_execz .LBB0_789
	s_sub_i32 s4, 21, s34
	s_and_b32 s5, s12, 7
	s_sub_i32 s6, s13, s5
	s_add_i32 s6, s6, 7
	s_lshr_b32 s6, s6, 3
	s_mul_i32 s6, s6, s4
	s_lshl_b32 s5, s5, 8
	v_mov_b32_e32 v0, s5
	v_mov_b32_e32 v1, 1
	global_atomic_add v1, v0, v1, s[68:69] sc0
	s_min_u32 s7, s13, 8
	s_mul_i32 s4, s7, s4
	v_mov_b32_e32 v0, 0
	s_waitcnt vmcnt(0)
	v_add_u32_e32 v1, 1, v1
	v_cmp_eq_u32_e32 vcc, s6, v1
	s_cbranch_vccz .Lgb_spin_s20
	v_mov_b32_e32 v1, 1
	global_atomic_add v0, v1, s[14:15]
